# pipelined global-attention loop: VALU re-spaced so the first two MFMA slots after each barrier carry no transcendental/VALU work (MFMA-first head), same instruction multiset and code size
# speedup vs baseline: 1.0180x; 1.0004x over previous
; template <bool TRACK> ...
;     ...
;         const int cur = j & 1; const int tl = j < n0 ? j : t1lo + (j - n0);
;         if (j + 1 < nt) { const int tn = (j + 1) < n0 ? (j + 1) : t1lo + (j + 1 - n0);
;             kreg = *(const u32x4*)(Kb + (size_t)(tn * 64 + srow) * 64 + sc * 8); vreg = *(const u32x4*)(Vtb + (size_t)srow * KEYS + tn * 64 + sc * 8); }
;         bool active = true; bool mt = masked && j >= n0; const int kpos0 = (tl - 4) * 64;
;         if (mt) { const int qs = qstart + wave * 32; active = !(kpos0 > qs + 31 + 128 || kpos0 + 63 < qs - 128);
;             if (kpos0 >= qs + 31 - 128 && kpos0 + 63 <= qs + 128) mt = false; }
;         if (active) {
;             const LAS unsigned char* Kbuf = lds + cur * 18432; const LAS unsigned char* Vbuf = Kbuf + 9216;
;             f32x16 s0 = negm, s1 = negm;
;             u32x2 vq[8];
;             if constexpr (!TRACK) {
;             bf16x8 kf[8];
; #pragma unroll
;             for (int d = 0; d < 4; ++d) { kf[2 * d] = *(const LAS bf16x8*)(Kbuf + (r32 * 72 + d * 16 + hi * 8) * 2); kf[2 * d + 1] = *(const LAS bf16x8*)(Kbuf + ((32 + r32) * 72 + d * 16 + hi * 8) * 2); }
;             __builtin_amdgcn_sched_barrier(0);
; #pragma unroll
;             for (int d = 0; d < 4; ++d) {
;                 s0 = __builtin_amdgcn_mfma_f32_32x32x16_bf16(kf[2 * d], qf[d], s0, 0, 0, 0);
;                 s1 = __builtin_amdgcn_mfma_f32_32x32x16_bf16(kf[2 * d + 1], qf[d], s1, 0, 0, 0);
;             }
; #pragma unroll
;             for (int kc = 0; kc < 2; ++kc) {
;                 const LAS unsigned char* vp0 = Vbuf + (r32 * 68 + kc * 16 + 4 * hi) * 2; const LAS unsigned char* vp1 = vp0 + 32 * 68 * 2;
;                 vq[4 * kc] = *(const LAS u32x2*)vp0; vq[4 * kc + 1] = *(const LAS u32x2*)(vp0 + 16); vq[4 * kc + 2] = *(const LAS u32x2*)vp1; vq[4 * kc + 3] = *(const LAS u32x2*)(vp1 + 16); }
;             __builtin_amdgcn_sched_barrier(0);
;             } else {
; #pragma unroll
;             for (int d = 0; d < 4; ++d) {
;                 const bf16x8 a0 = *(const LAS bf16x8*)(Kbuf + (r32 * 72 + d * 16 + hi * 8) * 2);
;                 const bf16x8 a1 = *(const LAS bf16x8*)(Kbuf + ((32 + r32) * 72 + d * 16 + hi * 8) * 2);
;                 s0 = __builtin_amdgcn_mfma_f32_32x32x16_bf16(a0, qf[d], s0, 0, 0, 0);
;                 s1 = __builtin_amdgcn_mfma_f32_32x32x16_bf16(a1, qf[d], s1, 0, 0, 0);
;             }
;     ...
; #pragma unroll
.Lnoprio_a:
.LBB0_167:
	global_load_dwordx4 v[98:101], v114, s[4:5]
	global_load_dwordx4 v[102:105], v116, s[38:39]
	ds_read_b128 v[106:109], v204 offset:18432
	ds_read_b128 v[110:113], v202 offset:18432
	ds_read_b128 v[158:161], v204 offset:18464
	ds_read2_b64 v[206:209], v247 offset0:128 offset1:130
	ds_read2_b64 v[210:213], v0 offset0:160 offset1:162
	s_add_u32 s4, s4, 0x2000
	s_addc_u32 s5, s5, 0
	s_add_u32 s38, s38, 0x80
	s_addc_u32 s39, s39, 0
	s_waitcnt lgkmcnt(4)
	v_mfma_f32_32x32x16_bf16 v[214:229], v[106:109], v[94:97], 0
	ds_read_b128 v[106:109], v202 offset:18464
	s_waitcnt lgkmcnt(4)
	v_mfma_f32_32x32x16_bf16 v[230:245], v[110:113], v[94:97], 0
	ds_read_b128 v[110:113], v204 offset:18496
	s_waitcnt lgkmcnt(4)
	v_mfma_f32_32x32x16_bf16 v[214:229], v[158:161], v[90:93], v[214:229]
	ds_read_b128 v[158:161], v202 offset:18496
	v_exp_f32_e32 v58, v58
	v_exp_f32_e32 v59, v59
	v_exp_f32_e32 v60, v60
	s_waitcnt lgkmcnt(2)
	v_mfma_f32_32x32x16_bf16 v[230:245], v[106:109], v[90:93], v[230:245]
	ds_read_b128 v[106:109], v204 offset:18528
	v_exp_f32_e32 v61, v61
	v_exp_f32_e32 v62, v62
	v_exp_f32_e32 v63, v63
	s_waitcnt lgkmcnt(2)
	v_mfma_f32_32x32x16_bf16 v[214:229], v[110:113], v[86:89], v[214:229]
	ds_read_b128 v[110:113], v202 offset:18528
	v_exp_f32_e32 v64, v64
	v_exp_f32_e32 v65, v65
	v_cvt_pk_bf16_f32 v54, v58, v59
	s_waitcnt lgkmcnt(2)
	v_mfma_f32_32x32x16_bf16 v[230:245], v[158:161], v[86:89], v[230:245]
	v_cvt_pk_bf16_f32 v55, v60, v61
	v_cvt_pk_bf16_f32 v56, v62, v63
	v_cvt_pk_bf16_f32 v57, v64, v65
	s_waitcnt lgkmcnt(1)
	v_mfma_f32_32x32x16_bf16 v[214:229], v[106:109], v[82:85], v[214:229]
	v_exp_f32_e32 v66, v66
	v_exp_f32_e32 v67, v67
	v_exp_f32_e32 v68, v68
	s_waitcnt lgkmcnt(0)
	v_mfma_f32_32x32x16_bf16 v[230:245], v[110:113], v[82:85], v[230:245]
	v_exp_f32_e32 v69, v69
	v_exp_f32_e32 v70, v70
	v_exp_f32_e32 v71, v71
	v_mfma_f32_32x32x16_bf16 v[2:17], v[206:209], v[50:53], v[2:17]
	ds_read2_b64 v[206:209], v247 offset0:132 offset1:134
	v_exp_f32_e32 v72, v72
	v_exp_f32_e32 v73, v73
	v_cvt_pk_bf16_f32 v66, v66, v67
	v_mfma_f32_32x32x16_bf16 v[18:33], v[210:213], v[50:53], v[18:33]
	ds_read2_b64 v[210:213], v0 offset0:164 offset1:166
	v_cvt_pk_bf16_f32 v67, v68, v69
	v_cvt_pk_bf16_f32 v68, v70, v71
	v_cvt_pk_bf16_f32 v69, v72, v73
	v_mfma_f32_4x4x4_16b_bf16 v[34:37], v[118:119], v[50:51], v[34:37]
	v_mfma_f32_4x4x4_16b_bf16 v[38:41], v[118:119], v[52:53], v[38:41]
	v_exp_f32_e32 v74, v74
	v_exp_f32_e32 v75, v75
	s_waitcnt lgkmcnt(1)
	v_mfma_f32_32x32x16_bf16 v[2:17], v[206:209], v[54:57], v[2:17]
	ds_read2_b64 v[206:209], v247 offset0:136 offset1:138
	v_exp_f32_e32 v76, v76
	v_exp_f32_e32 v77, v77
	v_exp_f32_e32 v78, v78
	s_waitcnt lgkmcnt(1)
	v_mfma_f32_32x32x16_bf16 v[18:33], v[210:213], v[54:57], v[18:33]
	ds_read2_b64 v[210:213], v0 offset0:168 offset1:170
	v_exp_f32_e32 v79, v79
	v_exp_f32_e32 v80, v80
	v_exp_f32_e32 v81, v81
	v_mfma_f32_4x4x4_16b_bf16 v[34:37], v[118:119], v[54:55], v[34:37]
	v_mfma_f32_4x4x4_16b_bf16 v[38:41], v[118:119], v[56:57], v[38:41]
	v_cvt_pk_bf16_f32 v70, v74, v75
	s_waitcnt vmcnt(1)
	ds_write_b128 v201, v[98:101] offset:0
	s_waitcnt vmcnt(0)
	ds_write2_b64 v127, v[102:103], v[104:105] offset1:1
	s_waitcnt lgkmcnt(3)
	v_mfma_f32_32x32x16_bf16 v[2:17], v[206:209], v[66:69], v[2:17]
	ds_read2_b64 v[206:209], v247 offset0:140 offset1:142
	v_cvt_pk_bf16_f32 v71, v76, v77
	v_cvt_pk_bf16_f32 v72, v78, v79
	v_cvt_pk_bf16_f32 v73, v80, v81
	s_waitcnt lgkmcnt(3)
	v_mfma_f32_32x32x16_bf16 v[18:33], v[210:213], v[66:69], v[18:33]
	ds_read2_b64 v[210:213], v0 offset0:172 offset1:174
	v_exp_f32_e32 v214, v214
	v_exp_f32_e32 v215, v215
	v_exp_f32_e32 v216, v216
	v_mfma_f32_4x4x4_16b_bf16 v[34:37], v[118:119], v[66:67], v[34:37]
	v_mfma_f32_4x4x4_16b_bf16 v[38:41], v[118:119], v[68:69], v[38:41]
	v_exp_f32_e32 v217, v217
	s_waitcnt lgkmcnt(1)
	v_mfma_f32_32x32x16_bf16 v[2:17], v[206:209], v[70:73], v[2:17]
	v_exp_f32_e32 v218, v218
	v_exp_f32_e32 v219, v219
	v_exp_f32_e32 v220, v220
	s_waitcnt lgkmcnt(0)
	v_mfma_f32_32x32x16_bf16 v[18:33], v[210:213], v[70:73], v[18:33]
	v_exp_f32_e32 v221, v221
	v_cvt_pk_bf16_f32 v214, v214, v215
	v_cvt_pk_bf16_f32 v215, v216, v217
	v_mfma_f32_4x4x4_16b_bf16 v[34:37], v[118:119], v[70:71], v[34:37]
	v_mfma_f32_4x4x4_16b_bf16 v[38:41], v[118:119], v[72:73], v[38:41]
	v_cvt_pk_bf16_f32 v216, v218, v219
	v_cvt_pk_bf16_f32 v217, v220, v221
	s_waitcnt lgkmcnt(0)
	s_barrier
; template <bool TRACK> ...
;     ...
;         const int cur = j & 1; const int tl = j < n0 ? j : t1lo + (j - n0);
;         if (j + 1 < nt) { const int tn = (j + 1) < n0 ? (j + 1) : t1lo + (j + 1 - n0);
;             kreg = *(const u32x4*)(Kb + (size_t)(tn * 64 + srow) * 64 + sc * 8); vreg = *(const u32x4*)(Vtb + (size_t)srow * KEYS + tn * 64 + sc * 8); }
;         bool active = true; bool mt = masked && j >= n0; const int kpos0 = (tl - 4) * 64;
;         if (mt) { const int qs = qstart + wave * 32; active = !(kpos0 > qs + 31 + 128 || kpos0 + 63 < qs - 128);
;             if (kpos0 >= qs + 31 - 128 && kpos0 + 63 <= qs + 128) mt = false; }
;         if (active) {
;             const LAS unsigned char* Kbuf = lds + cur * 18432; const LAS unsigned char* Vbuf = Kbuf + 9216;
;             f32x16 s0 = negm, s1 = negm;
;             u32x2 vq[8];
;             if constexpr (!TRACK) {
;             bf16x8 kf[8];
; #pragma unroll
;             for (int d = 0; d < 4; ++d) { kf[2 * d] = *(const LAS bf16x8*)(Kbuf + (r32 * 72 + d * 16 + hi * 8) * 2); kf[2 * d + 1] = *(const LAS bf16x8*)(Kbuf + ((32 + r32) * 72 + d * 16 + hi * 8) * 2); }
;             __builtin_amdgcn_sched_barrier(0);
; #pragma unroll
;             for (int d = 0; d < 4; ++d) {
;                 s0 = __builtin_amdgcn_mfma_f32_32x32x16_bf16(kf[2 * d], qf[d], s0, 0, 0, 0);
;                 s1 = __builtin_amdgcn_mfma_f32_32x32x16_bf16(kf[2 * d + 1], qf[d], s1, 0, 0, 0);
;             }
; #pragma unroll
;             for (int kc = 0; kc < 2; ++kc) {
;                 const LAS unsigned char* vp0 = Vbuf + (r32 * 68 + kc * 16 + 4 * hi) * 2; const LAS unsigned char* vp1 = vp0 + 32 * 68 * 2;
;                 vq[4 * kc] = *(const LAS u32x2*)vp0; vq[4 * kc + 1] = *(const LAS u32x2*)(vp0 + 16); vq[4 * kc + 2] = *(const LAS u32x2*)vp1; vq[4 * kc + 3] = *(const LAS u32x2*)(vp1 + 16); }
;             __builtin_amdgcn_sched_barrier(0);
;             } else {
; #pragma unroll
;             for (int d = 0; d < 4; ++d) {
;                 const bf16x8 a0 = *(const LAS bf16x8*)(Kbuf + (r32 * 72 + d * 16 + hi * 8) * 2);
;                 const bf16x8 a1 = *(const LAS bf16x8*)(Kbuf + ((32 + r32) * 72 + d * 16 + hi * 8) * 2);
;                 s0 = __builtin_amdgcn_mfma_f32_32x32x16_bf16(a0, qf[d], s0, 0, 0, 0);
;                 s1 = __builtin_amdgcn_mfma_f32_32x32x16_bf16(a1, qf[d], s1, 0, 0, 0);
;             }
;     ...
; #pragma unroll
	global_load_dwordx4 v[98:101], v114, s[4:5]
	global_load_dwordx4 v[102:105], v116, s[38:39]
	ds_read_b128 v[106:109], v204 offset:0
	ds_read_b128 v[110:113], v202 offset:0
	ds_read_b128 v[158:161], v204 offset:32
	ds_read2_b64 v[206:209], v123 offset0:128 offset1:130
	ds_read2_b64 v[210:213], v125 offset0:160 offset1:162
	s_add_u32 s4, s4, 0x2000
	s_addc_u32 s5, s5, 0
	s_add_u32 s38, s38, 0x80
	s_addc_u32 s39, s39, 0
	s_waitcnt lgkmcnt(4)
	v_mfma_f32_32x32x16_bf16 v[50:65], v[106:109], v[94:97], 0
	ds_read_b128 v[106:109], v202 offset:32
	s_waitcnt lgkmcnt(4)
	v_mfma_f32_32x32x16_bf16 v[66:81], v[110:113], v[94:97], 0
	ds_read_b128 v[110:113], v204 offset:64
	s_waitcnt lgkmcnt(4)
	v_mfma_f32_32x32x16_bf16 v[50:65], v[158:161], v[90:93], v[50:65]
	ds_read_b128 v[158:161], v202 offset:64
	v_exp_f32_e32 v222, v222
	v_exp_f32_e32 v223, v223
	v_exp_f32_e32 v224, v224
	s_waitcnt lgkmcnt(2)
	v_mfma_f32_32x32x16_bf16 v[66:81], v[106:109], v[90:93], v[66:81]
	ds_read_b128 v[106:109], v204 offset:96
	v_exp_f32_e32 v225, v225
	v_exp_f32_e32 v226, v226
	v_exp_f32_e32 v227, v227
	s_waitcnt lgkmcnt(2)
	v_mfma_f32_32x32x16_bf16 v[50:65], v[110:113], v[86:89], v[50:65]
	ds_read_b128 v[110:113], v202 offset:96
	v_exp_f32_e32 v228, v228
	v_exp_f32_e32 v229, v229
	v_cvt_pk_bf16_f32 v218, v222, v223
	s_waitcnt lgkmcnt(2)
	v_mfma_f32_32x32x16_bf16 v[66:81], v[158:161], v[86:89], v[66:81]
	v_cvt_pk_bf16_f32 v219, v224, v225
	v_cvt_pk_bf16_f32 v220, v226, v227
	v_cvt_pk_bf16_f32 v221, v228, v229
	s_waitcnt lgkmcnt(1)
	v_mfma_f32_32x32x16_bf16 v[50:65], v[106:109], v[82:85], v[50:65]
	v_exp_f32_e32 v230, v230
	v_exp_f32_e32 v231, v231
	v_exp_f32_e32 v232, v232
	s_waitcnt lgkmcnt(0)
	v_mfma_f32_32x32x16_bf16 v[66:81], v[110:113], v[82:85], v[66:81]
	v_exp_f32_e32 v233, v233
	v_exp_f32_e32 v234, v234
	v_exp_f32_e32 v235, v235
	v_mfma_f32_32x32x16_bf16 v[2:17], v[206:209], v[214:217], v[2:17]
	ds_read2_b64 v[206:209], v123 offset0:132 offset1:134
	v_exp_f32_e32 v236, v236
	v_exp_f32_e32 v237, v237
	v_cvt_pk_bf16_f32 v230, v230, v231
	v_mfma_f32_32x32x16_bf16 v[18:33], v[210:213], v[214:217], v[18:33]
	ds_read2_b64 v[210:213], v125 offset0:164 offset1:166
	v_cvt_pk_bf16_f32 v231, v232, v233
	v_cvt_pk_bf16_f32 v232, v234, v235
	v_cvt_pk_bf16_f32 v233, v236, v237
	v_mfma_f32_4x4x4_16b_bf16 v[34:37], v[118:119], v[214:215], v[34:37]
	v_mfma_f32_4x4x4_16b_bf16 v[38:41], v[118:119], v[216:217], v[38:41]
	v_exp_f32_e32 v238, v238
	v_exp_f32_e32 v239, v239
	s_waitcnt lgkmcnt(1)
	v_mfma_f32_32x32x16_bf16 v[2:17], v[206:209], v[218:221], v[2:17]
	ds_read2_b64 v[206:209], v123 offset0:136 offset1:138
	v_exp_f32_e32 v240, v240
	v_exp_f32_e32 v241, v241
	v_exp_f32_e32 v242, v242
	s_waitcnt lgkmcnt(1)
	v_mfma_f32_32x32x16_bf16 v[18:33], v[210:213], v[218:221], v[18:33]
	ds_read2_b64 v[210:213], v125 offset0:168 offset1:170
	v_exp_f32_e32 v243, v243
	v_exp_f32_e32 v244, v244
	v_exp_f32_e32 v245, v245
	v_mfma_f32_4x4x4_16b_bf16 v[34:37], v[118:119], v[218:219], v[34:37]
	v_mfma_f32_4x4x4_16b_bf16 v[38:41], v[118:119], v[220:221], v[38:41]
	v_cvt_pk_bf16_f32 v234, v238, v239
	s_waitcnt vmcnt(1)
	ds_write_b128 v201, v[98:101] offset:18432
	s_waitcnt vmcnt(0)
	ds_write2_b64 v129, v[102:103], v[104:105] offset1:1
	s_waitcnt lgkmcnt(3)
	v_mfma_f32_32x32x16_bf16 v[2:17], v[206:209], v[230:233], v[2:17]
	ds_read2_b64 v[206:209], v123 offset0:140 offset1:142
	v_cvt_pk_bf16_f32 v235, v240, v241
	v_cvt_pk_bf16_f32 v236, v242, v243
	v_cvt_pk_bf16_f32 v237, v244, v245
	s_waitcnt lgkmcnt(3)
	v_mfma_f32_32x32x16_bf16 v[18:33], v[210:213], v[230:233], v[18:33]
	ds_read2_b64 v[210:213], v125 offset0:172 offset1:174
	v_exp_f32_e32 v50, v50
	v_exp_f32_e32 v51, v51
	v_exp_f32_e32 v52, v52
	v_mfma_f32_4x4x4_16b_bf16 v[34:37], v[118:119], v[230:231], v[34:37]
	v_mfma_f32_4x4x4_16b_bf16 v[38:41], v[118:119], v[232:233], v[38:41]
	v_exp_f32_e32 v53, v53
	s_waitcnt lgkmcnt(1)
	v_mfma_f32_32x32x16_bf16 v[2:17], v[206:209], v[234:237], v[2:17]
	v_exp_f32_e32 v54, v54
	v_exp_f32_e32 v55, v55
	v_exp_f32_e32 v56, v56
	s_waitcnt lgkmcnt(0)
	v_mfma_f32_32x32x16_bf16 v[18:33], v[210:213], v[234:237], v[18:33]
	v_exp_f32_e32 v57, v57
	v_cvt_pk_bf16_f32 v50, v50, v51
	v_cvt_pk_bf16_f32 v51, v52, v53
	v_mfma_f32_4x4x4_16b_bf16 v[34:37], v[118:119], v[234:235], v[34:37]
	v_mfma_f32_4x4x4_16b_bf16 v[38:41], v[118:119], v[236:237], v[38:41]
	v_cvt_pk_bf16_f32 v52, v54, v55
	v_cvt_pk_bf16_f32 v53, v56, v57
	s_add_i32 s20, s20, 2
	s_cmp_lg_u32 s20, 36
	s_waitcnt lgkmcnt(0)
	s_barrier
	s_cbranch_scc1 .LBB0_167
	s_setprio 0
	s_nop 0
	s_nop 0
	s_nop 0
	s_nop 0
	s_nop 0
	s_nop 0
	s_nop 0
	s_nop 0
	s_nop 0
	s_nop 0
	s_nop 0
	s_nop 0
	s_nop 0
	s_nop 0
	s_nop 0
	s_nop 0
	s_nop 0
	s_nop 0
	s_nop 0
	s_nop 0
	s_nop 0
	s_nop 0
	s_nop 0
	s_nop 0
	s_nop 0
	s_nop 0
	s_nop 0
	global_load_dwordx4 v[214:217], v[154:155], off offset:1280
	global_load_dwordx4 v[218:221], v[150:151], off offset:1280
	global_load_dwordx4 v[222:225], v[142:143], off offset:1280
	global_load_dwordx4 v[226:229], v[138:139], off offset:1280
	s_mov_b64 s[4:5], 0x2000
	s_mov_b64 s[38:39], 0x80
	s_nop 15
	v_readlane_b32 s89, v248, 3
	v_add_f32_e32 v34, v34, v38
	s_nop 0
	ds_bpermute_b32 v35, v188, v34
	s_waitcnt lgkmcnt(0)
	v_add_f32_e32 v34, v34, v35
	s_nop 0
	v_div_scale_f32 v0, s[20:21], v34, v34, 1.0
	v_rcp_f32_e32 v35, v0
	s_waitcnt lgkmcnt(0)
	s_barrier
; #define LAS __attribute__((address_space(3)))
; __device__ __forceinline__ unsigned pk2(float lo, float hi) { f32x2_t v = {lo, hi}; bf16x2_t b = __builtin_convertvector(v, bf16x2_t); return __builtin_bit_cast(unsigned, b); }
; __device__ __forceinline__ float silu_f(float v) { return v * __builtin_amdgcn_rcpf(1.0f + __expf(-v)); }
; template <bool TRACK> ...
;     ...
;     const float ltot = TRACK ? lsum + __shfl_xor(lsum, 32) : lacc[0]; const float inv = 1.0f / ltot;
;     {
;         LAS unsigned char* scr = lds + 40960 + wave * 8704;
; #pragma unroll
;         for (int dh = 0; dh < 2; ++dh)
; #pragma unroll
;             for (int rg = 0; rg < 4; ++rg) { const int d = dh * 32 + 8 * rg + 4 * hi;
;                 f32x4 ov; ov.x = (dh == 0 ? o0[4 * rg] : o1[4 * rg]) * inv; ov.y = (dh == 0 ? o0[4 * rg + 1] : o1[4 * rg + 1]) * inv; ov.z = (dh == 0 ? o0[4 * rg + 2] : o1[4 * rg + 2]) * inv; ov.w = (dh == 0 ? o0[4 * rg + 3] : o1[4 * rg + 3]) * inv;
;                 *(LAS f32x4*)(scr + r32 * 272 + d * 4) = ov; }
;         const int pc = lane & 7;
; #pragma unroll
;         for (int i = 0; i < 4; ++i) { const int rw = i * 8 + (lane >> 3), row = wave * 32 + rw;
;             const f32x4 oa = *(const LAS f32x4*)(scr + rw * 272 + pc * 32), ob = *(const LAS f32x4*)(scr + rw * 272 + pc * 32 + 16);
;             float gv[8]; unpack8(*(const u32x4*)(gate + (size_t)row * INW + 8 * pc), gv);
;             u32x4 w; w.x = pk2(oa.x * silu_f(gv[0]), oa.y * silu_f(gv[1])); w.y = pk2(oa.z * silu_f(gv[2]), oa.w * silu_f(gv[3]));
;             w.z = pk2(ob.x * silu_f(gv[4]), ob.y * silu_f(gv[5])); w.w = pk2(ob.z * silu_f(gv[6]), ob.w * silu_f(gv[7]));
;             *(u32x4*)(outp + (size_t)row * DM + 8 * pc) = w; }
	v_fma_f32 v36, -v0, v35, 1.0
	v_fmac_f32_e32 v35, v36, v35
	v_div_scale_f32 v36, vcc, 1.0, v34, 1.0
	v_mul_f32_e32 v37, v36, v35
	v_fma_f32 v38, -v0, v37, v36
	v_fmac_f32_e32 v37, v38, v35
	v_fma_f32 v0, -v0, v37, v36
	v_div_fmas_f32 v0, v0, v35, v37
	v_div_fixup_f32 v0, v0, v34, 1.0
	s_nop 1
	v_mul_f32_e64 v2, v2, v0
	v_mul_f32_e64 v3, v3, v0
	v_pk_mul_f32 v[4:5], v[4:5], v[0:1] op_sel_hi:[1,0]
	v_add_u32_e32 v34, v198, v156
	ds_write_b128 v34, v[2:5] offset:40960
	v_pk_mul_f32 v[2:3], v[6:7], v[0:1] op_sel_hi:[1,0]
	v_pk_mul_f32 v[4:5], v[8:9], v[0:1] op_sel_hi:[1,0]
	ds_write_b128 v34, v[2:5] offset:40992
	v_pk_mul_f32 v[2:3], v[10:11], v[0:1] op_sel_hi:[1,0]
	v_pk_mul_f32 v[4:5], v[12:13], v[0:1] op_sel_hi:[1,0]
	ds_write_b128 v34, v[2:5] offset:41024
	v_pk_mul_f32 v[2:3], v[14:15], v[0:1] op_sel_hi:[1,0]
	v_pk_mul_f32 v[4:5], v[16:17], v[0:1] op_sel_hi:[1,0]
	ds_write_b128 v34, v[2:5] offset:41056
	v_pk_mul_f32 v[2:3], v[18:19], v[0:1] op_sel_hi:[1,0]
	v_pk_mul_f32 v[4:5], v[20:21], v[0:1] op_sel_hi:[1,0]
	ds_write_b128 v34, v[2:5] offset:41088
	v_pk_mul_f32 v[2:3], v[22:23], v[0:1] op_sel_hi:[1,0]
	v_pk_mul_f32 v[4:5], v[24:25], v[0:1] op_sel_hi:[1,0]
	ds_write_b128 v34, v[2:5] offset:41120
	v_pk_mul_f32 v[2:3], v[26:27], v[0:1] op_sel_hi:[1,0]
	v_pk_mul_f32 v[4:5], v[28:29], v[0:1] op_sel_hi:[1,0]
	ds_write_b128 v34, v[2:5] offset:41152
	v_pk_mul_f32 v[2:3], v[30:31], v[0:1] op_sel_hi:[1,0]
	v_pk_mul_f32 v[4:5], v[32:33], v[0:1] op_sel_hi:[1,0]
	ds_write_b128 v34, v[2:5] offset:41184
	v_add_u32_e32 v0, v192, v193
	ds_read_b128 v[6:9], v0 offset:40960
	ds_read_b128 v[2:5], v0 offset:40976
	s_waitcnt vmcnt(3)
	v_lshlrev_b32_e32 v14, 16, v214
	v_and_b32_e32 v15, 0xffff0000, v214
	v_mul_f32_e32 v214, 0xbfb8aa3b, v14
	v_exp_f32_e32 v214, v214
	s_nop 0
	v_add_f32_e32 v214, 1.0, v214
	v_rcp_f32_e32 v16, v214
	v_mul_f32_e32 v214, 0xbfb8aa3b, v15
	v_exp_f32_e32 v214, v214
	s_nop 0
	v_add_f32_e32 v214, 1.0, v214
	v_rcp_f32_e32 v17, v214
	v_lshlrev_b32_e32 v214, 16, v215
	v_and_b32_e32 v215, 0xffff0000, v215
	v_pk_mul_f32 v[14:15], v[16:17], v[14:15]
	s_waitcnt lgkmcnt(1)
	v_pk_mul_f32 v[6:7], v[6:7], v[14:15]
	s_nop 0
	v_cvt_pk_bf16_f32 v6, v6, v7
	v_mul_f32_e32 v7, 0xbfb8aa3b, v214
	v_exp_f32_e32 v7, v7
	s_nop 0
	v_add_f32_e32 v7, 1.0, v7
	v_rcp_f32_e32 v14, v7
	v_mul_f32_e32 v7, 0xbfb8aa3b, v215
	v_exp_f32_e32 v7, v7
	s_nop 0
	v_add_f32_e32 v7, 1.0, v7
	v_rcp_f32_e32 v15, v7
	s_nop 0
	v_pk_mul_f32 v[214:215], v[14:15], v[214:215]
	s_nop 0
	v_pk_mul_f32 v[8:9], v[8:9], v[214:215]
	s_nop 0
	v_cvt_pk_bf16_f32 v7, v8, v9
	v_lshlrev_b32_e32 v8, 16, v216
	v_and_b32_e32 v9, 0xffff0000, v216
	v_mul_f32_e32 v214, 0xbfb8aa3b, v8
	v_mul_f32_e32 v215, 0xbfb8aa3b, v9
	v_exp_f32_e32 v214, v214
	v_exp_f32_e32 v215, v215
	v_add_f32_e32 v214, 1.0, v214
	v_add_f32_e32 v215, 1.0, v215
	v_rcp_f32_e32 v214, v214
	v_rcp_f32_e32 v215, v215
	s_nop 0
	v_pk_mul_f32 v[8:9], v[214:215], v[8:9]
	s_waitcnt lgkmcnt(0)
	v_pk_mul_f32 v[2:3], v[2:3], v[8:9]
	s_nop 0
	v_cvt_pk_bf16_f32 v8, v2, v3
	v_lshlrev_b32_e32 v2, 16, v217
	v_mul_f32_e32 v9, 0xbfb8aa3b, v2
	v_exp_f32_e32 v9, v9
	v_and_b32_e32 v3, 0xffff0000, v217
	v_add_f32_e32 v9, 1.0, v9
	v_rcp_f32_e32 v214, v9
	v_mul_f32_e32 v9, 0xbfb8aa3b, v3
	v_exp_f32_e32 v9, v9
	s_nop 0
	v_add_f32_e32 v9, 1.0, v9
	v_rcp_f32_e32 v215, v9
	s_nop 0
	v_pk_mul_f32 v[2:3], v[214:215], v[2:3]
	s_nop 0
	v_pk_mul_f32 v[2:3], v[4:5], v[2:3]
	s_nop 0
	v_cvt_pk_bf16_f32 v9, v2, v3
	global_store_dwordx4 v[152:153], v[6:9], off
	ds_read_b128 v[6:9], v0 offset:43136
	ds_read_b128 v[2:5], v0 offset:43152
	s_waitcnt vmcnt(3)
	v_lshlrev_b32_e32 v14, 16, v218
	v_and_b32_e32 v15, 0xffff0000, v218
	v_mul_f32_e32 v218, 0xbfb8aa3b, v14
	v_exp_f32_e32 v218, v218
	s_nop 0
	v_add_f32_e32 v218, 1.0, v218
	v_rcp_f32_e32 v16, v218
	v_mul_f32_e32 v218, 0xbfb8aa3b, v15
	v_exp_f32_e32 v218, v218
	s_nop 0
	v_add_f32_e32 v218, 1.0, v218
	v_rcp_f32_e32 v17, v218
	v_lshlrev_b32_e32 v218, 16, v219
	v_and_b32_e32 v219, 0xffff0000, v219
	v_pk_mul_f32 v[14:15], v[16:17], v[14:15]
	s_waitcnt lgkmcnt(1)
	v_pk_mul_f32 v[6:7], v[6:7], v[14:15]
	s_nop 0
	v_cvt_pk_bf16_f32 v6, v6, v7
	v_mul_f32_e32 v7, 0xbfb8aa3b, v218
	v_exp_f32_e32 v7, v7
	s_nop 0
	v_add_f32_e32 v7, 1.0, v7
	v_rcp_f32_e32 v14, v7
	v_mul_f32_e32 v7, 0xbfb8aa3b, v219
	v_exp_f32_e32 v7, v7
	s_nop 0
	v_add_f32_e32 v7, 1.0, v7
	v_rcp_f32_e32 v15, v7
	s_nop 0
	v_pk_mul_f32 v[218:219], v[14:15], v[218:219]
	s_nop 0
	v_pk_mul_f32 v[8:9], v[8:9], v[218:219]
	s_nop 0
	v_cvt_pk_bf16_f32 v7, v8, v9
	v_lshlrev_b32_e32 v8, 16, v220
	v_and_b32_e32 v9, 0xffff0000, v220
	v_mul_f32_e32 v218, 0xbfb8aa3b, v8
	v_mul_f32_e32 v219, 0xbfb8aa3b, v9
	v_exp_f32_e32 v218, v218
	v_exp_f32_e32 v219, v219
	v_add_f32_e32 v218, 1.0, v218
	v_add_f32_e32 v219, 1.0, v219
	v_rcp_f32_e32 v218, v218
	v_rcp_f32_e32 v219, v219
	s_nop 0
	v_pk_mul_f32 v[8:9], v[218:219], v[8:9]
	s_waitcnt lgkmcnt(0)
; #define LAS __attribute__((address_space(3)))
; __device__ __forceinline__ unsigned pk2(float lo, float hi) { f32x2_t v = {lo, hi}; bf16x2_t b = __builtin_convertvector(v, bf16x2_t); return __builtin_bit_cast(unsigned, b); }
; __device__ __forceinline__ float silu_f(float v) { return v * __builtin_amdgcn_rcpf(1.0f + __expf(-v)); }
; template <bool TRACK> ...
;     ...
;         for (int i = 0; i < 4; ++i) { const int rw = i * 8 + (lane >> 3), row = wave * 32 + rw;
;             const f32x4 oa = *(const LAS f32x4*)(scr + rw * 272 + pc * 32), ob = *(const LAS f32x4*)(scr + rw * 272 + pc * 32 + 16);
;             float gv[8]; unpack8(*(const u32x4*)(gate + (size_t)row * INW + 8 * pc), gv);
;             u32x4 w; w.x = pk2(oa.x * silu_f(gv[0]), oa.y * silu_f(gv[1])); w.y = pk2(oa.z * silu_f(gv[2]), oa.w * silu_f(gv[3]));
;             w.z = pk2(ob.x * silu_f(gv[4]), ob.y * silu_f(gv[5])); w.w = pk2(ob.z * silu_f(gv[6]), ob.w * silu_f(gv[7]));
;             *(u32x4*)(outp + (size_t)row * DM + 8 * pc) = w; }
	v_pk_mul_f32 v[2:3], v[2:3], v[8:9]
	s_nop 0
	v_cvt_pk_bf16_f32 v8, v2, v3
	v_lshlrev_b32_e32 v2, 16, v221
	v_mul_f32_e32 v9, 0xbfb8aa3b, v2
	v_exp_f32_e32 v9, v9
	v_and_b32_e32 v3, 0xffff0000, v221
	v_add_f32_e32 v9, 1.0, v9
	v_rcp_f32_e32 v218, v9
	v_mul_f32_e32 v9, 0xbfb8aa3b, v3
	v_exp_f32_e32 v9, v9
	s_nop 0
	v_add_f32_e32 v9, 1.0, v9
	v_rcp_f32_e32 v219, v9
	s_nop 0
	v_pk_mul_f32 v[2:3], v[218:219], v[2:3]
	s_nop 0
	v_pk_mul_f32 v[2:3], v[4:5], v[2:3]
	s_nop 0
	v_cvt_pk_bf16_f32 v9, v2, v3
	global_store_dwordx4 v[144:145], v[6:9], off
	ds_read_b128 v[6:9], v0 offset:45312
	ds_read_b128 v[2:5], v0 offset:45328
	s_waitcnt vmcnt(3)
	v_lshlrev_b32_e32 v14, 16, v222
	v_and_b32_e32 v15, 0xffff0000, v222
	v_mul_f32_e32 v222, 0xbfb8aa3b, v14
	v_exp_f32_e32 v222, v222
	s_nop 0
	v_add_f32_e32 v222, 1.0, v222
	v_rcp_f32_e32 v16, v222
	v_mul_f32_e32 v222, 0xbfb8aa3b, v15
	v_exp_f32_e32 v222, v222
	s_nop 0
	v_add_f32_e32 v222, 1.0, v222
	v_rcp_f32_e32 v17, v222
	v_lshlrev_b32_e32 v222, 16, v223
	v_and_b32_e32 v223, 0xffff0000, v223
	v_pk_mul_f32 v[14:15], v[16:17], v[14:15]
	s_waitcnt lgkmcnt(1)
	v_pk_mul_f32 v[6:7], v[6:7], v[14:15]
	s_nop 0
	v_cvt_pk_bf16_f32 v6, v6, v7
	v_mul_f32_e32 v7, 0xbfb8aa3b, v222
	v_exp_f32_e32 v7, v7
	s_nop 0
	v_add_f32_e32 v7, 1.0, v7
	v_rcp_f32_e32 v14, v7
	v_mul_f32_e32 v7, 0xbfb8aa3b, v223
	v_exp_f32_e32 v7, v7
	s_nop 0
	v_add_f32_e32 v7, 1.0, v7
	v_rcp_f32_e32 v15, v7
	s_nop 0
	v_pk_mul_f32 v[222:223], v[14:15], v[222:223]
	s_nop 0
	v_pk_mul_f32 v[8:9], v[8:9], v[222:223]
	s_nop 0
	v_cvt_pk_bf16_f32 v7, v8, v9
	v_lshlrev_b32_e32 v8, 16, v224
	v_and_b32_e32 v9, 0xffff0000, v224
	v_mul_f32_e32 v222, 0xbfb8aa3b, v8
	v_mul_f32_e32 v223, 0xbfb8aa3b, v9
	v_exp_f32_e32 v222, v222
	v_exp_f32_e32 v223, v223
	v_add_f32_e32 v222, 1.0, v222
	v_add_f32_e32 v223, 1.0, v223
	v_rcp_f32_e32 v222, v222
	v_rcp_f32_e32 v223, v223
	s_nop 0
	v_pk_mul_f32 v[8:9], v[222:223], v[8:9]
	s_waitcnt lgkmcnt(0)
	v_pk_mul_f32 v[2:3], v[2:3], v[8:9]
	s_nop 0
	v_cvt_pk_bf16_f32 v8, v2, v3
	v_lshlrev_b32_e32 v2, 16, v225
	v_mul_f32_e32 v9, 0xbfb8aa3b, v2
	v_exp_f32_e32 v9, v9
	v_and_b32_e32 v3, 0xffff0000, v225
	v_add_f32_e32 v9, 1.0, v9
	v_rcp_f32_e32 v222, v9
	v_mul_f32_e32 v9, 0xbfb8aa3b, v3
	v_exp_f32_e32 v9, v9
	s_nop 0
	v_add_f32_e32 v9, 1.0, v9
	v_rcp_f32_e32 v223, v9
	s_nop 0
	v_pk_mul_f32 v[2:3], v[222:223], v[2:3]
	s_nop 0
	v_pk_mul_f32 v[2:3], v[4:5], v[2:3]
	s_nop 0
	v_cvt_pk_bf16_f32 v9, v2, v3
	global_store_dwordx4 v[140:141], v[6:9], off
	ds_read_b128 v[6:9], v0 offset:47488
	ds_read_b128 v[2:5], v0 offset:47504
	s_waitcnt vmcnt(3)
	v_lshlrev_b32_e32 v14, 16, v226
	v_mul_f32_e32 v0, 0xbfb8aa3b, v14
	v_exp_f32_e32 v0, v0
	v_and_b32_e32 v15, 0xffff0000, v226
	v_lshlrev_b32_e32 v226, 16, v227
	v_and_b32_e32 v227, 0xffff0000, v227
	v_add_f32_e32 v0, 1.0, v0
	v_rcp_f32_e32 v16, v0
	v_mul_f32_e32 v0, 0xbfb8aa3b, v15
	v_exp_f32_e32 v0, v0
	s_nop 0
	v_add_f32_e32 v0, 1.0, v0
	v_rcp_f32_e32 v17, v0
	v_mul_f32_e32 v0, 0xbfb8aa3b, v226
	v_exp_f32_e32 v0, v0
	v_pk_mul_f32 v[14:15], v[16:17], v[14:15]
	s_waitcnt lgkmcnt(1)
	v_pk_mul_f32 v[6:7], v[6:7], v[14:15]
	v_add_f32_e32 v0, 1.0, v0
	v_rcp_f32_e32 v14, v0
	v_mul_f32_e32 v0, 0xbfb8aa3b, v227
	v_exp_f32_e32 v0, v0
	v_cvt_pk_bf16_f32 v6, v6, v7
	v_add_f32_e32 v0, 1.0, v0
	v_rcp_f32_e32 v15, v0
	s_nop 0
	v_pk_mul_f32 v[226:227], v[14:15], v[226:227]
	s_nop 0
	v_pk_mul_f32 v[8:9], v[8:9], v[226:227]
	s_nop 0
	v_cvt_pk_bf16_f32 v7, v8, v9
	v_lshlrev_b32_e32 v8, 16, v228
	v_mul_f32_e32 v0, 0xbfb8aa3b, v8
	v_exp_f32_e32 v0, v0
	v_and_b32_e32 v9, 0xffff0000, v228
	v_add_f32_e32 v0, 1.0, v0
	v_rcp_f32_e32 v226, v0
	v_mul_f32_e32 v0, 0xbfb8aa3b, v9
	v_exp_f32_e32 v0, v0
	s_nop 0
	v_add_f32_e32 v0, 1.0, v0
	v_rcp_f32_e32 v227, v0
	s_nop 0
	v_pk_mul_f32 v[8:9], v[226:227], v[8:9]
	s_waitcnt lgkmcnt(0)
	v_pk_mul_f32 v[2:3], v[2:3], v[8:9]
	s_nop 0
	v_cvt_pk_bf16_f32 v8, v2, v3
	v_lshlrev_b32_e32 v2, 16, v229
	v_mul_f32_e32 v0, 0xbfb8aa3b, v2
	v_exp_f32_e32 v0, v0
	v_and_b32_e32 v3, 0xffff0000, v229
	v_add_f32_e32 v0, 1.0, v0
	v_rcp_f32_e32 v226, v0
	v_mul_f32_e32 v0, 0xbfb8aa3b, v3
	v_exp_f32_e32 v0, v0
	s_nop 0
	v_add_f32_e32 v0, 1.0, v0
	v_rcp_f32_e32 v227, v0
	s_nop 0
	v_pk_mul_f32 v[2:3], v[226:227], v[2:3]
	s_nop 0
	v_pk_mul_f32 v[2:3], v[4:5], v[2:3]
	s_nop 0
	v_cvt_pk_bf16_f32 v9, v2, v3
	global_store_dwordx4 v[136:137], v[6:9], off
